# v17 + w_dn weight conversion moved from the GU-tail workers to the attention-phase idle WGs (balances the two idle windows)
# speedup vs baseline: 1.0078x; 1.0016x over previous
; #define LAS __attribute__((address_space(3)))
; #define LAS __attribute__((address_space(3)))
; #define LDS_WAIT() asm volatile("s_waitcnt lgkmcnt(0)" ::: "memory")
; __device__ __forceinline__ unsigned pk2(float lo, float hi) { return pg8::cvt_pk_bf16(lo, hi); }
; __device__ __forceinline__ void p0_transpose_item(const float* W, int ldw, int K, const float* gain, bf16* WT, int n0src, int n0dst, int k0, LAS float* scr, int lane) {
;     ...
;     for (int i = 0; i < 32; ++i) {
;         const int kk = 2 * i + (lane >> 5);
;         float w = __builtin_nontemporal_load(&W[(size_t)(k0 + kk) * ldw + n0src + (lane & 31)]);
;         if (gain) w *= gain[k0 + kk];
;         scr[kk * 33 + (lane & 31)] = w;
;     }
;     LDS_WAIT(); asm volatile("" ::: "memory");
;     const int c = lane & 7;
; #pragma unroll
;     for (int j = 0; j < 4; ++j) {
;         const int n = (lane >> 3) + 8 * j; const LAS float* s = scr + (8 * c) * 33 + n;
;         v4u o; o.x = pk2(s[0 * 33], s[1 * 33]); o.y = pk2(s[2 * 33], s[3 * 33]); o.z = pk2(s[4 * 33], s[5 * 33]); o.w = pk2(s[6 * 33], s[7 * 33]);
; __global__ void __launch_bounds__(NWAVES * 64, 2) hymba_fwd(Args args) {
;     ...
;                 if (l + 1 < DEPTH && blockIdx.x >= 48) {
;                     int ln = lane, tn = tid; asm volatile("" : "+v"(ln), "+v"(tn));
;                     const int wk = ((int)blockIdx.x - 48) * NWAVES + wave, nwk = (G - 48) * NWAVES;
;                     convert_layer_weights(args, ws, (LAS float*)(lds + wave * 16384), l + 1, wk, nwk, ln, 12);
;                     convert_layer_caches(args, ws, (LAS float*)(lds + wave * 16384), l + 1, wk, nwk, ((int)blockIdx.x - 48) * (NWAVES * 64) + tn, (G - 48) * NWAVES * 64, ln);
.LBB0_46:
	s_cmp_gt_i32 s54, 15
	v_readlane_b32 s2, v255, 5
	s_cselect_b64 s[0:1], -1, 0
	v_readlane_b32 s3, v255, 6
	s_or_b64 s[0:1], s[2:3], s[0:1]
	s_and_b64 vcc, exec, s[0:1]
	s_cbranch_vccnz .LBB0_204
	v_readlane_b32 s0, v255, 19
	v_readlane_b32 s1, v255, 20
	s_add_i32 s4, s0, 1
	v_readlane_b32 s0, v251, 9
	v_and_b32_e32 v55, 63, v216
	v_mov_b32_e32 v1, v216
	v_readlane_b32 s1, v251, 10
	s_andn2_b64 vcc, exec, s[0:1]
	v_ashrrev_i32_e32 v18, 5, v55
	v_ashrrev_i32_e32 v19, 3, v55
	v_lshlrev_b32_e32 v0, 3, v55
	s_movk_i32 s0, 0x84
	v_mul_lo_u32 v20, v18, s0
	v_add_u32_e32 v21, 2, v18
	v_add_u32_e32 v22, 4, v18
	v_add_u32_e32 v23, 6, v18
	v_add_u32_e32 v24, 8, v18
	v_add_u32_e32 v25, 10, v18
	v_add_u32_e32 v26, 12, v18
	v_add_u32_e32 v27, 14, v18
	v_add_u32_e32 v28, 16, v18
	v_add_u32_e32 v29, 18, v18
	v_add_u32_e32 v30, 20, v18
	v_add_u32_e32 v31, 22, v18
	v_add_u32_e32 v32, 24, v18
	v_add_u32_e32 v33, 26, v18
	v_add_u32_e32 v34, 28, v18
	v_add_u32_e32 v35, 30, v18
	v_add_u32_e32 v36, 32, v18
	v_add_u32_e32 v37, 34, v18
	v_add_u32_e32 v38, 36, v18
	v_add_u32_e32 v39, 38, v18
	v_add_u32_e32 v40, 40, v18
	v_add_u32_e32 v41, 42, v18
	v_add_u32_e32 v42, 44, v18
	v_add_u32_e32 v43, 46, v18
	v_add_u32_e32 v44, 48, v18
	v_add_u32_e32 v45, 50, v18
	v_add_u32_e32 v46, 52, v18
	v_add_u32_e32 v47, 54, v18
	v_add_u32_e32 v48, 56, v18
	v_add_u32_e32 v49, 58, v18
	v_add_u32_e32 v50, 60, v18
	v_add_u32_e32 v51, 62, v18
	v_and_b32_e32 v0, 56, v0
	v_lshlrev_b32_e32 v56, 2, v19
	v_add_u32_e32 v52, 8, v19
	v_add_u32_e32 v53, 16, v19
	v_add_u32_e32 v54, 24, v19
	v_readlane_b32 s6, v251, 14
	s_cbranch_vccnz .LBB0_191
	s_lshl_b32 s100, s4, 8
	s_or_b32 s100, s100, 0x300004
	s_mov_b32 s101, 1
	s_branch .Lcvt_entry

; #define LAS __attribute__((address_space(3)))
; #define LAS __attribute__((address_space(3)))
; __global__ void __launch_bounds__(NWAVES * 64, 2) hymba_fwd(Args args) {
;     ...
;                 if (l + 1 < DEPTH && blockIdx.x >= 64) {
;                     int ln = lane; asm volatile("" : "+v"(ln));
;                     convert_layer_weights(args, ws, (LAS float*)(lds + wave * 16384), l + 1, ((int)blockIdx.x - 64) * NWAVES + wave, (G - 64) * NWAVES, ln, 3);
;                     if (l == 0) { int tn = tid; asm volatile("" : "+v"(tn)); copy_window_outputs(args, ((int)blockIdx.x - 64) * (NWAVES * 64) + tn, (G - 64) * NWAVES * 64); }
;                 }
.LBB0_294:
	v_readlane_b32 s2, v251, 31
	s_cmp_gt_i32 s54, 15
	v_readlane_b32 s3, v251, 32
	s_cselect_b64 s[0:1], -1, 0
	s_xor_b64 s[2:3], s[2:3], -1
	s_or_b64 s[0:1], s[2:3], s[0:1]
	v_readlane_b32 s94, v255, 12
	s_and_b64 vcc, exec, s[0:1]
	v_readlane_b32 s92, v255, 11
	v_readlane_b32 s95, v255, 13
	v_readlane_b32 s6, v251, 40
	v_readlane_b32 s93, v255, 16
	v_readlane_b32 s18, v254, 30
	v_readlane_b32 s19, v254, 35
	s_movk_i32 s29, 0x5800
	s_cbranch_vccnz .LBB0_440
	v_readlane_b32 s0, v251, 33
	v_readlane_b32 s1, v251, 34
	v_and_b32_e32 v0, 63, v216
	s_andn2_b64 vcc, exec, s[0:1]
	s_nop 0
	v_readlane_b32 s100, v255, 19
	s_add_i32 s100, s100, 1
	s_lshl_b32 s100, s100, 8
	s_or_b32 s100, s100, 0x40000b
	s_mov_b32 s101, 3
	s_branch .Lcvt_entry
